# chunk-state items: dt preparation spread over all 8 waves (one chain per wave, DPP scan) inside the conv stage's first load wait instead of 2400 instructions on wave 0; on top of scalarised conv row l
# baseline (speedup 1.0000x reference)
.LBB0_648:
	s_ashr_i32 s4, s42, 2
	v_mov_b32_e32 v164, v195
	s_lshl_b32 s43, s4, 7
	v_readfirstlane_b32 s3, v164
	v_and_b32_e32 v162, 63, v164
	s_cmp_gt_u32 s3, 63
	v_lshrrev_b32_e32 v163, 3, v162
	s_lshr_b32 s60, s3, 6
	s_lshr_b32 s61, s60, 2
	s_and_b32 s62, s60, 3
	s_lshl_b32 s63, s61, 4
	s_add_i32 s62, s62, s63
	s_add_i32 s62, s62, s9
	s_mul_i32 s63, s61, 0x7f
	v_lshlrev_b32_e32 v200, 1, v162
	v_or_b32_e32 v201, 1, v200
	v_xor_b32_e32 v200, s63, v200
	v_xor_b32_e32 v201, s63, v201
	v_lshlrev_b32_e32 v202, 7, v200
	v_lshlrev_b32_e32 v203, 7, v201
	v_mov_b32_e32 v204, 0
	s_lshl_b32 s64, s43, 7
	s_lshl_b32 s65, s62, 2
	s_add_u32 s64, s64, s65
	s_add_u32 s66, s30, 0xe752000
	s_addc_u32 s67, s31, 0
	s_add_u32 s66, s66, s64
	s_addc_u32 s67, s67, 0
	global_load_dword v196, v202, s[66:67]
	global_load_dword v197, v203, s[66:67]
	v_readlane_b32 s68, v254, 11
	v_readlane_b32 s69, v254, 12
	v_readlane_b32 s70, v254, 13
	v_readlane_b32 s71, v254, 14
	s_nop 1
	s_add_u32 s68, s68, s65
	s_addc_u32 s69, s69, 0
	s_add_u32 s70, s70, s65
	s_addc_u32 s71, s71, 0
	global_load_dword v198, v204, s[68:69]
	global_load_dword v199, v204, s[70:71]

.Lcs3_done:
	s_cmp_lg_u32 s47, 0
	s_cbranch_scc1 .Ldt3_skip
	s_mov_b64 s[98:99], exec
	s_mov_b64 exec, -1
	s_waitcnt vmcnt(12)
	v_add_f32_e32 v196, v196, v198
	v_add_f32_e32 v197, v197, v198
	v_mul_f32_e32 v205, 0x3fb8aa3b, v199
	v_exp_f32_e32 v205, v205
	v_and_b32_e32 v206, 0x7fffffff, v196
	v_and_b32_e32 v207, 0x7fffffff, v197
	v_mul_f32_e32 v205, 0xbfb8aa3b, v205
	v_mul_f32_e32 v206, 0xbfb8aa3b, v206
	v_mul_f32_e32 v207, 0xbfb8aa3b, v207
	v_exp_f32_e32 v206, v206
	v_exp_f32_e32 v207, v207
	s_nop 0
	v_add_f32_e32 v208, 1.0, v206
	v_add_f32_e32 v210, 1.0, v207
	v_log_f32_e32 v209, v208
	v_log_f32_e32 v211, v210
	v_add_f32_e32 v212, -1.0, v208
	v_add_f32_e32 v213, -1.0, v210
	v_rcp_f32_e32 v212, v212
	v_rcp_f32_e32 v213, v213
	v_mul_f32_e32 v209, 0x3f317218, v209
	v_mul_f32_e32 v211, 0x3f317218, v211
	v_mul_f32_e32 v212, v206, v212
	v_mul_f32_e32 v213, v207, v213
	v_mul_f32_e32 v209, v209, v212
	v_mul_f32_e32 v211, v211, v213
	v_cmp_eq_f32_e32 vcc, 1.0, v208
	v_cndmask_b32_e32 v209, v209, v206, vcc
	v_cmp_eq_f32_e32 vcc, 1.0, v210
	v_cndmask_b32_e32 v211, v211, v207, vcc
	v_max_f32_e32 v196, 0, v196
	v_max_f32_e32 v197, 0, v197
	v_add_f32_e32 v208, v196, v209
	v_add_f32_e32 v210, v197, v211
	v_mul_f32_e32 v212, v208, v205
	v_fma_f32 v213, v210, v205, v212
	v_mov_b32_e32 v214, v213
	s_nop 1
	v_add_f32_dpp v214, v214, v214 row_shr:1 row_mask:0xf bank_mask:0xf
	s_nop 1
	v_add_f32_dpp v214, v214, v214 row_shr:2 row_mask:0xf bank_mask:0xf
	s_nop 1
	v_add_f32_dpp v214, v214, v214 row_shr:4 row_mask:0xf bank_mask:0xf
	s_nop 1
	v_add_f32_dpp v214, v214, v214 row_shr:8 row_mask:0xf bank_mask:0xf
	s_nop 1
	v_add_f32_dpp v214, v214, v214 row_bcast:15 row_mask:0xa bank_mask:0xf
	s_nop 1
	v_add_f32_dpp v214, v214, v214 row_bcast:31 row_mask:0xc bank_mask:0xf
	s_nop 0
	v_sub_f32_e32 v215, v214, v213
	v_fma_f32 v209, v208, v205, v215
	v_fma_f32 v211, v210, v205, v209
	v_readfirstlane_b32 s48, v195
	s_nop 0
	s_lshr_b32 s48, s48, 6
	s_lshl_b32 s49, s48, 9
	v_lshl_add_u32 v216, v200, 2, s49
	v_lshl_add_u32 v221, v201, 2, s49
	v_add_u32_e32 v217, 0x1f800, v216
	v_add_u32_e32 v218, 0x20800, v216
	v_add_u32_e32 v222, 0x1f800, v221
	v_add_u32_e32 v223, 0x20800, v221
	ds_write_b32 v217, v208
	ds_write_b32 v218, v209
	ds_write_b32 v222, v210
	ds_write_b32 v223, v211
	s_lshr_b32 s49, s48, 2
	s_lshl_b32 s49, s49, 4
	s_and_b32 s101, s48, 3
	s_add_i32 s49, s49, s101
	s_add_i32 s49, s49, s9
	s_lshl_b32 s49, s49, 3
	s_ashr_i32 s100, s42, 2
	s_lshl_b32 s100, s100, 15
	s_add_u32 s100, s100, s49
	s_add_u32 s100, s100, 0xe9d2000
	s_add_u32 s100, s30, s100
	s_addc_u32 s101, s31, 0
	v_lshlrev_b32_e32 v219, 8, v200
	v_lshlrev_b32_e32 v220, 8, v201
	global_store_dwordx2 v219, v[208:209], s[100:101]
	global_store_dwordx2 v220, v[210:211], s[100:101]
	s_mov_b64 exec, s[98:99]

.LBB0_947:
	s_or_b64 exec, exec, s[0:1]
	s_waitcnt vmcnt(1)
	v_mov_b32_e32 v1, v195
	s_cmpk_lt_i32 s2, 0x200
	s_waitcnt lgkmcnt(0)
	s_barrier
	s_nop 0
	s_nop 0
	s_nop 0
	s_nop 0
	s_nop 0
	s_nop 0
	s_nop 0
	s_nop 0
	s_nop 0
	s_nop 0
	s_cselect_b64 s[4:5], -1, 0
	s_cmpk_gt_i32 s2, 0x1ff
	v_readfirstlane_b32 s3, v1
	s_cbranch_scc1 .LBB0_950
	s_and_b32 s8, s2, 7
	s_bfe_u32 s1, s2, 0x50003
	s_cmpk_gt_i32 s2, 0xff
	s_cbranch_scc0 .LBB0_951
	s_lshl_b32 s0, s8, 1
	s_bfe_u32 s6, s2, 0x10003
	s_or_b32 s0, s0, s6
	s_lshr_b32 s73, s1, 3
	s_or_b32 s0, s0, 64
	s_bfe_u32 s38, s2, 0x20004
	s_cmp_gt_u32 s1, 15
	s_cselect_b32 s6, 0x2800000, 0
	s_lshl_b32 s12, s73, 10
	s_mov_b32 s11, 0
	s_and_b32 s7, s12, 0x400
	s_or_b32 s10, s6, s7
	s_mov_b32 s13, s11
	s_mov_b32 s74, 8
	s_cbranch_execz .LBB0_952
	s_branch .LBB0_953
